# hand-scheduled attention inner loop: unroll x3, -m folded into QK acc init, max3 tree, no v_mov rotation, deep LDS prefetch
# speedup vs baseline: 1.0802x; 1.0802x over previous
; DI int tid512() { int t = threadIdx.x; asm volatile("" : "+v"(t)); return t; }
; #define A_LOAD(KB) { _Pragma("unroll") for (int i = 0; i < 2; ++i) { rk[i] = *(const u32x4*)(kp + (size_t)((KB) * 64 + 32 * i) * 1024); rv[i] = *(const u32x4*)(vp + (size_t)(64 * i) * TOK + (KB) * 64); } }
; #define A_STORE(STG) { char* D_ = smem + (STG) * ST; _Pragma("unroll") for (int i = 0; i < 2; ++i) { *(u32x4*)(D_ + ksoff + i * 32 * 272) = rk[i]; \
;       u32x2 lo2_ = {rv[i].x, rv[i].y}, hi2_ = {rv[i].z, rv[i].w}; *(u32x2*)(D_ + vsoff + i * 64 * VROW) = lo2_; *(u32x2*)(D_ + vsoff + i * 64 * VROW + 16) = hi2_; } }
; DI void attn_block(const Params& p, int layer, int hd, int q0, int nkeys, char* smem) {
;   constexpr int KT = 64 * 272, VROW = 144, ST = KT + 128 * VROW;
;   const int t = tid512(), lane = t & 63, w = t >> 6, mp = w >> 2, wq = w & 3, r = lane & 31, h = lane >> 5;
;   const bf16_t* DQ = (const bf16_t*)(p.ws + O_DQ);
;   const bf16_t* DK = (const bf16_t*)(p.ws + O_DK);
;   const bf16_t* DVT = (const bf16_t*)(p.ws + O_DVT);
;   const float* scal = (const float*)(p.ws + O_SCAL);
;   const int q = q0 + 32 * wq + r;
;   bf16x8 qf[4];
; #pragma unroll
;   for (int s = 0; s < 4; ++s) qf[s] = *(const bf16x8*)(DQ + (size_t)q * 1024 + hd * 128 + 64 * mp + 16 * s + 8 * h);
;   const int nkb = nkeys >> 6, lastkb = nkb - 1;
;   const bf16_t* kp = DK + (size_t)(t >> 4) * 1024 + hd * 128 + (t & 15) * 8;
;   const int ksoff = (t >> 4) * 272 + (t & 15) * 16;
;   const bf16_t* vp = DVT + (size_t)(hd * 128 + (t >> 3)) * TOK + (t & 7) * 8;
;   const int vsoff = KT + (t >> 3) * VROW + ((t & 7) >> 1) * 32 + (t & 1) * 8;
;   u32x4 rk[2], rv[2];
;     ...
;   A_LOAD(0);
;   __syncthreads();
;   A_STORE(0);
;   A_LOAD(lastkb < 1 ? lastkb : 1);
;   A_STORE(1);
;   A_LOAD(lastkb < 2 ? lastkb : 2);
;   __syncthreads();
;   float m = -1e30f, l = 0.f;
;   f32x16 o[4];
; #pragma unroll
;   for (int vt = 0; vt < 4; ++vt)
; #pragma unroll
;     for (int i = 0; i < 16; ++i) o[vt][i] = 0.f;
;   f32x16 sc[2], sn[2];
;   A_SCORES(sc, 0);
.LBB0_392:
	s_lshl_b32 s4, s6, 7
	v_mov_b32_e32 v202, v0
	s_and_b32 s4, s4, 0x1f80
	s_addk_i32 s4, 0x100
	v_lshrrev_b32_e32 v2, 1, v202
	v_and_b32_e32 v200, 31, v202
	v_and_b32_e32 v201, 0x60, v2
	v_or3_b32 v198, v200, s4, v201
	v_readlane_b32 s4, v254, 9
	v_lshlrev_b32_e32 v180, 11, v198
	v_readlane_b32 s5, v254, 10
	v_ashrrev_i32_e32 v199, 8, v202
	v_lshlrev_b32_e32 v4, 6, v199
	v_lshl_add_u64 v[2:3], s[4:5], 0, v[180:181]
	s_lshl_b32 s4, s6, 1
	s_and_b32 s94, s4, 0x7fffff80
	s_lshl_b32 s22, s94, 1
	v_bfe_u32 v193, v202, 5, 1
	v_lshl_add_u64 v[2:3], v[2:3], 0, s[22:23]
	v_ashrrev_i32_e32 v5, 31, v4
	v_lshl_add_u64 v[2:3], v[4:5], 1, v[2:3]
	v_lshlrev_b32_e32 v180, 4, v193
	v_ashrrev_i32_e32 v34, 4, v202
	v_lshl_add_u64 v[2:3], v[2:3], 0, v[180:181]
	v_ashrrev_i32_e32 v35, 31, v34
	v_readlane_b32 s4, v254, 11
	global_load_dwordx4 v[130:133], v[2:3], off
	global_load_dwordx4 v[134:137], v[2:3], off offset:32
	global_load_dwordx4 v[138:141], v[2:3], off offset:64
	global_load_dwordx4 v[142:145], v[2:3], off offset:96
	v_lshlrev_b64 v[2:3], 11, v[34:35]
	v_readlane_b32 s5, v254, 12
	v_lshlrev_b32_e32 v35, 4, v202
	v_and_b32_e32 v36, 0xf0, v35
	v_lshl_add_u64 v[2:3], s[4:5], 0, v[2:3]
	v_lshl_add_u64 v[2:3], v[2:3], 0, s[22:23]
	v_mov_b32_e32 v37, v181
	v_readlane_b32 s4, v253, 54
	v_lshl_add_u64 v[162:163], v[2:3], 0, v[36:37]
	v_ashrrev_i32_e32 v37, 3, v202
	v_readlane_b32 s5, v253, 55
	v_add_u32_e32 v4, s94, v37
	v_mov_b32_e32 v5, v181
	v_mov_b64_e32 v[2:3], s[4:5]
	v_mad_i64_i32 v[2:3], s[4:5], v4, s29, v[2:3]
	v_and_b32_e32 v4, 7, v202
	v_lshlrev_b32_e32 v4, 4, v4
	v_add_co_u32_e32 v10, vcc, s46, v162
	v_lshl_add_u64 v[164:165], v[2:3], 0, v[4:5]
	s_nop 0
	v_addc_co_u32_e32 v11, vcc, 0, v163, vcc
	v_add_co_u32_e32 v38, vcc, s30, v164
	global_load_dwordx4 v[2:5], v[162:163], off
	global_load_dwordx4 v[6:9], v[164:165], off
	v_addc_co_u32_e32 v39, vcc, 0, v165, vcc
	v_add_co_u32_e32 v18, vcc, s87, v162
	global_load_dwordx4 v[10:13], v[10:11], off
	s_nop 0
	global_load_dwordx4 v[14:17], v[38:39], off
	v_addc_co_u32_e32 v19, vcc, 0, v163, vcc
	v_add_co_u32_e32 v26, vcc, s47, v162
	s_waitcnt vmcnt(63) expcnt(7) lgkmcnt(15)
	s_barrier
	global_load_dwordx4 v[18:21], v[18:19], off
	s_nop 0
	global_load_dwordx4 v[22:25], v[164:165], off offset:128
	v_addc_co_u32_e32 v27, vcc, 0, v163, vcc
	global_load_dwordx4 v[26:29], v[26:27], off
	s_nop 0
	global_load_dwordx4 v[30:33], v[38:39], off offset:128
	v_lshlrev_b32_e32 v40, 3, v202
	v_mul_lo_u32 v37, v37, s28
	s_movk_i32 s4, 0x110
	v_and_b32_e32 v35, 0x60, v35
	v_mad_u64_u32 v[194:195], s[4:5], v34, s4, v[36:37]
	v_and_or_b32 v34, v40, 8, v37
	v_add_u32_e32 v205, v34, v35
	v_add_u32_e32 v36, 16, v194
	v_add_u32_e32 v34, 16, v205
	v_add_u32_e32 v35, 0x4000, v34
	v_add_u32_e32 v37, 0x6800, v34
	v_add_u32_e32 v40, 0xd000, v34
	global_load_dwordx4 v[146:149], v[164:165], off offset:256
	s_mov_b32 s4, 0x50000
	s_mov_b32 s42, 1
	v_mul_u32_u24_e32 v203, 0x90, v200
	v_mov_b32_e32 v204, 0xf149f2ca
	v_mov_b32_e32 v195, 0
	s_waitcnt vmcnt(0)
	ds_write_b128 v36, v[2:5]
	ds_write2_b64 v35, v[6:7], v[8:9] offset0:128 offset1:130
	ds_write_b128 v36, v[10:13] offset:8704
	ds_write2_b64 v37, v[14:15], v[16:17] offset1:2
	ds_write_b128 v36, v[18:21] offset:35840
	ds_write2_b64 v40, v[22:23], v[24:25] offset1:2
	ds_write_b128 v36, v[26:29] offset:44544
	v_add_u32_e32 v2, 0xf000, v34
	ds_write2_b64 v2, v[30:31], v[32:33] offset0:128 offset1:130
	v_add_co_u32_e32 v2, vcc, s84, v162
	global_load_dwordx4 v[150:153], v[38:39], off offset:256
	s_nop 0
	v_addc_co_u32_e32 v3, vcc, 0, v163, vcc
	v_add_co_u32_e32 v4, vcc, s4, v162
	s_mov_b32 s4, 0
	s_nop 0
	v_addc_co_u32_e32 v5, vcc, 0, v163, vcc
	global_load_dwordx4 v[158:161], v[2:3], off
	global_load_dwordx4 v[154:157], v[4:5], off
	v_lshl_add_u32 v2, v199, 7, 16
	v_mul_u32_u24_e32 v3, 0x110, v200
	v_add3_u32 v206, v2, v180, v3
	s_waitcnt lgkmcnt(0)
	s_barrier
	ds_read_b128 v[2:5], v206
	ds_read_b128 v[6:9], v206 offset:32
	s_waitcnt lgkmcnt(1)
	v_mfma_f32_32x32x16_bf16 v[114:129], v[2:5], v[130:133], 0
	s_mov_b32 s18, s4
	s_mov_b32 s19, s4
	s_mov_b32 s5, s4
	s_mov_b32 s6, s4
	s_mov_b32 s7, s4
	s_mov_b32 s8, s4
	s_mov_b32 s9, s4
	s_waitcnt lgkmcnt(0)
	v_mfma_f32_32x32x16_bf16 v[114:129], v[6:9], v[134:137], v[114:129]
	ds_read_b128 v[2:5], v206 offset:64
	ds_read_b128 v[6:9], v206 offset:96
	s_mov_b32 s10, s4
	s_mov_b32 s11, s4
	s_mov_b32 s12, s4
	s_mov_b32 s13, s4
	s_mov_b32 s14, s4
	s_mov_b32 s15, s4
	s_waitcnt lgkmcnt(1)
	v_mfma_f32_32x32x16_bf16 v[114:129], v[2:5], v[138:141], v[114:129]
	ds_read_b128 v[2:5], v206 offset:8704
	ds_read_b128 v[10:13], v206 offset:8736
	s_mov_b32 s16, s4
	s_mov_b32 s17, s4
	v_mov_b64_e32 v[64:65], s[18:19]
	v_mov_b64_e32 v[50:51], s[4:5]
	v_mov_b64_e32 v[62:63], s[16:17]
	v_mov_b64_e32 v[60:61], s[14:15]
	s_waitcnt lgkmcnt(1)
	v_mfma_f32_32x32x16_bf16 v[98:113], v[2:5], v[130:133], 0
	ds_read_b128 v[2:5], v206 offset:8768
	v_mov_b64_e32 v[58:59], s[12:13]
	v_mov_b64_e32 v[56:57], s[10:11]
	v_mov_b64_e32 v[54:55], s[8:9]
	v_mov_b64_e32 v[52:53], s[6:7]
	v_mov_b64_e32 v[18:19], v[50:51]
	v_mov_b64_e32 v[34:35], v[50:51]
	s_waitcnt lgkmcnt(1)
	v_mfma_f32_32x32x16_bf16 v[98:113], v[10:13], v[134:137], v[98:113]
	s_mov_b32 s5, 2
	v_mov_b64_e32 v[20:21], v[52:53]
	v_mov_b64_e32 v[22:23], v[54:55]
	v_mov_b64_e32 v[24:25], v[56:57]
	v_mov_b64_e32 v[26:27], v[58:59]
	v_mov_b64_e32 v[28:29], v[60:61]
	v_mov_b64_e32 v[30:31], v[62:63]
	v_mfma_f32_32x32x16_bf16 v[114:129], v[6:9], v[142:145], v[114:129]
	ds_read_b128 v[6:9], v206 offset:8800
	v_mov_b64_e32 v[32:33], v[64:65]
	v_mov_b64_e32 v[36:37], v[52:53]
	v_mov_b64_e32 v[38:39], v[54:55]
	v_mov_b64_e32 v[40:41], v[56:57]
	v_mov_b64_e32 v[42:43], v[58:59]
	v_mov_b64_e32 v[44:45], v[60:61]
	s_waitcnt lgkmcnt(1)
; DI float ex2(float x) { return __builtin_amdgcn_exp2f(x); }
; #define A_LOAD(KB) { _Pragma("unroll") for (int i = 0; i < 2; ++i) { rk[i] = *(const u32x4*)(kp + (size_t)((KB) * 64 + 32 * i) * 1024); rv[i] = *(const u32x4*)(vp + (size_t)(64 * i) * TOK + (KB) * 64); } }
; #define A_STORE(STG) { char* D_ = smem + (STG) * ST; _Pragma("unroll") for (int i = 0; i < 2; ++i) { *(u32x4*)(D_ + ksoff + i * 32 * 272) = rk[i]; \
;       u32x2 lo2_ = {rv[i].x, rv[i].y}, hi2_ = {rv[i].z, rv[i].w}; *(u32x2*)(D_ + vsoff + i * 64 * VROW) = lo2_; *(u32x2*)(D_ + vsoff + i * 64 * VROW + 16) = hi2_; } }
; #define A_SCORES(DST, STG) { const char* Ks_ = smem + (STG) * ST; _Pragma("unroll") for (int kt = 0; kt < 2; ++kt) { \
;       _Pragma("unroll") for (int i = 0; i < 16; ++i) DST[kt][i] = 0.f; \
;       _Pragma("unroll") for (int s = 0; s < 4; ++s) { const bf16x8 a_ = *(const bf16x8*)(Ks_ + (32 * kt + r) * 272 + 128 * mp + 32 * s + 16 * h); DST[kt] = MFMA32(a_, qf[s], DST[kt]); } } }
; DI void attn_block(const Params& p, int layer, int hd, int q0, int nkeys, char* smem) {
;     ...
;   float m = -1e30f, l = 0.f;
;   f32x16 o[4];
; #pragma unroll
;   for (int vt = 0; vt < 4; ++vt)
; #pragma unroll
;     for (int i = 0; i < 16; ++i) o[vt][i] = 0.f;
;   f32x16 sc[2], sn[2];
;   A_SCORES(sc, 0);
;   int c0 = 0, c1 = 1, c2 = 2;
;   for (int kb = 0; kb < nkb; ++kb) {
;     const char* Vs = smem + c0 * ST + KT;
;     A_STORE(c2);
;     A_LOAD((kb + 3 < lastkb) ? kb + 3 : lastkb);
;     if (kb + 1 < nkb) A_SCORES(sn, c1);
;     float mx = fmaxf(sc[0][0], sc[1][0]);
; #pragma unroll
;     for (int i = 1; i < 16; ++i) mx = fmaxf(mx, fmaxf(sc[0][i], sc[1][i]));
;     {
;       const auto pr_ = __builtin_amdgcn_permlane32_swap(__float_as_uint(mx), __float_as_uint(mx), false, false);
;       mx = fmaxf(__uint_as_float(pr_[0]), __uint_as_float(pr_[1]));
;     }
;     if (__any(mx > m + 8.f)) {
;       const float mn = (mx > m + 8.f) ? mx : m;
;       const float alpha = ex2(m - mn);
;       l *= alpha;
; #pragma unroll
;       for (int vt = 0; vt < 4; ++vt)
; #pragma unroll
;         for (int i = 0; i < 16; ++i) o[vt][i] *= alpha;
;       m = mn;
;     }
;     bf16x8 va[2][4];
;     const char* vbase = Vs + r * VROW + 16 * h;
; #pragma unroll
;     for (int vt = 0; vt < 4; ++vt) va[0][vt] = *(const bf16x8*)(vbase + 32 * vt * VROW);
	v_mfma_f32_32x32x16_bf16 v[98:113], v[2:5], v[138:141], v[98:113]
	v_mov_b64_e32 v[46:47], v[62:63]
	v_mov_b64_e32 v[48:49], v[64:65]
	s_waitcnt lgkmcnt(0)
	v_mfma_f32_32x32x16_bf16 v[98:113], v[6:9], v[142:145], v[98:113]
	v_mov_b64_e32 v[2:3], v[50:51]
	v_mov_b64_e32 v[4:5], v[52:53]
	v_mov_b64_e32 v[6:7], v[54:55]
	v_mov_b64_e32 v[8:9], v[56:57]
	v_mov_b64_e32 v[10:11], v[58:59]
	v_mov_b64_e32 v[12:13], v[60:61]
	v_mov_b64_e32 v[14:15], v[62:63]
	v_mov_b64_e32 v[16:17], v[64:65]
	v_mov_b32_e32 v196, 0x1a410
	v_lshl_add_u32 v196, v0, 2, v196
	ds_write_b32 v196, v170 offset:0
	ds_write_b32 v196, v171 offset:2048
	ds_write_b32 v196, v172 offset:4096
	ds_write_b32 v196, v173 offset:6144
	ds_write_b32 v196, v174 offset:8192
	ds_write_b32 v196, v175 offset:10240
	ds_write_b32 v196, v176 offset:12288
	ds_write_b32 v196, v177 offset:14336
	v_readfirstlane_b32 s52, v162
	v_readfirstlane_b32 s53, v163
	v_readfirstlane_b32 s56, v164
	v_readfirstlane_b32 s57, v165
	s_nop 3
	s_add_u32 s54, s52, s46
	s_addc_u32 s55, s53, 0
	s_add_u32 s58, s56, s30
	s_addc_u32 s59, s57, 0
	v_subrev_u32_e32 v175, s52, v162
	v_subrev_u32_e32 v176, s56, v164
	v_add_u32_e32 v162, 0x11800, v206
	v_add3_u32 v163, v203, v180, 16
	v_add_u32_e32 v174, 0x11810, v205
	v_add_u32_e32 v165, 0x11810, v194
	v_add_u32_e32 v164, 0xd000, v163
	s_mov_b32 s6, 0
	s_nop 7
	v_max3_f32 v246, v114, v115, v116
	v_max3_f32 v247, v117, v118, v119
	v_max3_f32 v246, v246, v120, v121
	v_max3_f32 v247, v247, v122, v123
	v_max3_f32 v246, v246, v124, v125
	v_max3_f32 v247, v247, v126, v127
	v_max3_f32 v246, v246, v128, v129
	v_max3_f32 v247, v247, v98, v99
	v_max3_f32 v246, v246, v100, v101
	v_max3_f32 v247, v247, v102, v103
	v_max3_f32 v246, v246, v104, v105
	v_max3_f32 v247, v247, v106, v107
	v_max3_f32 v246, v246, v108, v109
	v_max3_f32 v247, v247, v110, v111
	v_max3_f32 v246, v246, v112, v113
	v_max_f32_e32 v246, v246, v247
	v_mov_b32_e32 v247, v246
	s_nop 1
	v_permlane32_swap_b32_e32 v246, v247
	v_max_f32_e32 v246, v246, v247
	v_sub_f32_e32 v114, v114, v246
	v_sub_f32_e32 v115, v115, v246
	v_sub_f32_e32 v116, v116, v246
	v_sub_f32_e32 v117, v117, v246
	v_sub_f32_e32 v118, v118, v246
	v_sub_f32_e32 v119, v119, v246
	v_sub_f32_e32 v120, v120, v246
	v_sub_f32_e32 v121, v121, v246
	v_sub_f32_e32 v122, v122, v246
	v_sub_f32_e32 v123, v123, v246
	v_sub_f32_e32 v124, v124, v246
	v_sub_f32_e32 v125, v125, v246
	v_sub_f32_e32 v126, v126, v246
	v_sub_f32_e32 v127, v127, v246
	v_sub_f32_e32 v128, v128, v246
	v_sub_f32_e32 v129, v129, v246
	v_sub_f32_e32 v98, v98, v246
	v_sub_f32_e32 v99, v99, v246
	v_sub_f32_e32 v100, v100, v246
	v_sub_f32_e32 v101, v101, v246
	v_sub_f32_e32 v102, v102, v246
	v_sub_f32_e32 v103, v103, v246
	v_sub_f32_e32 v104, v104, v246
	v_sub_f32_e32 v105, v105, v246
	v_sub_f32_e32 v106, v106, v246
	v_sub_f32_e32 v107, v107, v246
	v_sub_f32_e32 v108, v108, v246
	v_sub_f32_e32 v109, v109, v246
	v_sub_f32_e32 v110, v110, v246
	v_sub_f32_e32 v111, v111, v246
	v_sub_f32_e32 v112, v112, v246
	v_sub_f32_e32 v113, v113, v246
	v_mul_f32_e32 v66, -1.0, v246
	v_mov_b32_e32 v197, 0
	v_mov_b32_e32 v207, 0
	v_mov_b32_e32 v67, v66
	v_mov_b32_e32 v68, v66
	v_mov_b32_e32 v69, v66
	v_mov_b32_e32 v70, v66
	v_mov_b32_e32 v71, v66
	v_mov_b32_e32 v72, v66
	v_mov_b32_e32 v73, v66
	v_mov_b32_e32 v74, v66
	v_mov_b32_e32 v75, v66
	v_mov_b32_e32 v76, v66
	v_mov_b32_e32 v77, v66
	v_mov_b32_e32 v78, v66
	v_mov_b32_e32 v79, v66
	v_mov_b32_e32 v80, v66
	v_mov_b32_e32 v81, v66
	s_waitcnt lgkmcnt(0)
	ds_read_b128 v[220:223], v163 offset:17408
	ds_read_b128 v[208:211], v206 offset:35840
	ds_read_b128 v[224:227], v163 offset:22016
	ds_read_b128 v[212:215], v206 offset:35872
	ds_read_b128 v[228:231], v163 offset:26624
	ds_read_b128 v[216:219], v206 offset:35904
	ds_read_b128 v[238:241], v163 offset:31232
.Lat_top_0:
	s_waitcnt lgkmcnt(5)
	v_mfma_f32_32x32x16_bf16 v[82:97], v[208:211], v[130:133], v[66:81]
	ds_read_b128 v[208:211], v206 offset:35936
	s_waitcnt vmcnt(0)
	ds_write_b128 v165, v[158:161] offset:0
	ds_write_b128 v165, v[154:157] offset:8704
	v_exp_f32_e32 v246, v114
	v_exp_f32_e32 v247, v115
	v_exp_f32_e32 v248, v116
	v_exp_f32_e32 v249, v117
	v_add_f32_e32 v197, v197, v246
	s_waitcnt lgkmcnt(6)
	v_mfma_f32_32x32x16_bf16 v[82:97], v[212:215], v[134:137], v[82:97]
	s_min_i32 s60, s6, 0x80
	s_add_i32 s60, s60, 3
	v_lshl_add_u32 v177, s60, 17, v175
	ds_write_b64 v174, v[146:147] offset:17408
	ds_write_b64 v174, v[148:149] offset:17424
	global_load_dwordx4 v[158:161], v177, s[52:53]
	global_load_dwordx4 v[154:157], v177, s[54:55]
	v_add_f32_e32 v207, v207, v247
	v_cvt_pk_bf16_f32 v242, v246, v247
	v_exp_f32_e32 v250, v118
	v_add_f32_e32 v197, v197, v248
	v_add_f32_e32 v207, v207, v249
	s_waitcnt lgkmcnt(6)
	v_mfma_f32_32x32x16_bf16 v[82:97], v[216:219], v[138:141], v[82:97]
	v_lshl_add_u32 v177, s60, 7, v176
	ds_write_b64 v174, v[150:151] offset:26624
	ds_write_b64 v174, v[152:153] offset:26640
	global_load_dwordx4 v[146:149], v177, s[56:57]
	global_load_dwordx4 v[150:153], v177, s[58:59]
	v_cvt_pk_bf16_f32 v243, v248, v249
	v_exp_f32_e32 v251, v119
	v_exp_f32_e32 v237, v120
	v_add_f32_e32 v197, v197, v250
	v_exp_f32_e32 v196, v121
	s_waitcnt lgkmcnt(6)
; #define MFMA32(a, b, c) __builtin_amdgcn_mfma_f32_32x32x16_bf16((a), (b), (c), 0, 0, 0)
; DI float ex2(float x) { return __builtin_amdgcn_exp2f(x); }
; #define A_LOAD(KB) { _Pragma("unroll") for (int i = 0; i < 2; ++i) { rk[i] = *(const u32x4*)(kp + (size_t)((KB) * 64 + 32 * i) * 1024); rv[i] = *(const u32x4*)(vp + (size_t)(64 * i) * TOK + (KB) * 64); } }
; DI void attn_block(const Params& p, int layer, int hd, int q0, int nkeys, char* smem) {
;     ...
;   for (int kb = 0; kb < nkb; ++kb) {
;     const char* Vs = smem + c0 * ST + KT;
;     A_STORE(c2);
;     A_LOAD((kb + 3 < lastkb) ? kb + 3 : lastkb);
;     if (kb + 1 < nkb) A_SCORES(sn, c1);
;     float mx = fmaxf(sc[0][0], sc[1][0]);
; #pragma unroll
;     for (int i = 1; i < 16; ++i) mx = fmaxf(mx, fmaxf(sc[0][i], sc[1][i]));
;     {
;       const auto pr_ = __builtin_amdgcn_permlane32_swap(__float_as_uint(mx), __float_as_uint(mx), false, false);
;       mx = fmaxf(__uint_as_float(pr_[0]), __uint_as_float(pr_[1]));
;     }
;     if (__any(mx > m + 8.f)) {
;       const float mn = (mx > m + 8.f) ? mx : m;
;       const float alpha = ex2(m - mn);
;       l *= alpha;
; #pragma unroll
;       for (int vt = 0; vt < 4; ++vt)
; #pragma unroll
;         for (int i = 0; i < 16; ++i) o[vt][i] *= alpha;
;       m = mn;
;     }
;     bf16x8 va[2][4];
;     const char* vbase = Vs + r * VROW + 16 * h;
; #pragma unroll
;     for (int vt = 0; vt < 4; ++vt) va[0][vt] = *(const bf16x8*)(vbase + 32 * vt * VROW);
;     float ls[4] = {0.f, 0.f, 0.f, 0.f};
; #pragma unroll
;     for (int st = 0; st < 4; ++st) {
;       if (st < 3) {
; #pragma unroll
;         for (int vt = 0; vt < 4; ++vt) va[(st + 1) & 1][vt] = *(const bf16x8*)(vbase + 32 * vt * VROW + (st + 1) * 32);
;       }
;       float pv[8];
; #pragma unroll
;       for (int i = 0; i < 8; ++i) { pv[i] = ex2(sc[st >> 1][8 * (st & 1) + i] - m); ls[i & 3] += pv[i]; }
;       u32x4 pk; pk.x = pack2(pv[0], pv[1]); pk.y = pack2(pv[2], pv[3]); pk.z = pack2(pv[4], pv[5]); pk.w = pack2(pv[6], pv[7]);
;       const bf16x8 pb = __builtin_bit_cast(bf16x8, pk);
; #pragma unroll
;       for (int vt = 0; vt < 4; ++vt) o[vt] = MFMA32(va[st & 1][vt], pb, o[vt]);
;     }
;     l += (ls[0] + ls[1]) + (ls[2] + ls[3]);
;     __syncthreads();
;     sc[0] = sn[0]; sc[1] = sn[1];
;     { const int tmp = c0; c0 = c1; c1 = c2; c2 = tmp; }
	v_mfma_f32_32x32x16_bf16 v[82:97], v[208:211], v[142:145], v[82:97]
	v_add_f32_e32 v207, v207, v251
	v_cvt_pk_bf16_f32 v244, v250, v251
	v_cvt_pk_bf16_f32 v245, v237, v196
	v_add_f32_e32 v197, v197, v237
	v_add_f32_e32 v207, v207, v196
	v_mfma_f32_32x32x16_bf16 v[34:49], v[220:223], v[242:245], v[34:49]
	ds_read_b128 v[220:223], v163 offset:17440
	v_exp_f32_e32 v246, v122
	v_exp_f32_e32 v247, v123
	v_exp_f32_e32 v248, v124
	v_exp_f32_e32 v249, v125
	v_add_f32_e32 v197, v197, v246
	v_mfma_f32_32x32x16_bf16 v[18:33], v[224:227], v[242:245], v[18:33]
	ds_read_b128 v[224:227], v163 offset:22048
	v_add_f32_e32 v207, v207, v247
	v_cvt_pk_bf16_f32 v170, v246, v247
	v_exp_f32_e32 v250, v126
	v_add_f32_e32 v197, v197, v248
	v_add_f32_e32 v207, v207, v249
	v_mfma_f32_32x32x16_bf16 v[2:17], v[228:231], v[242:245], v[2:17]
	ds_read_b128 v[228:231], v163 offset:26656
	v_cvt_pk_bf16_f32 v171, v248, v249
	v_exp_f32_e32 v251, v127
	v_exp_f32_e32 v237, v128
	v_add_f32_e32 v197, v197, v250
	v_exp_f32_e32 v196, v129
	v_mfma_f32_32x32x16_bf16 v[50:65], v[238:241], v[242:245], v[50:65]
	ds_read_b128 v[238:241], v163 offset:31264
	v_add_f32_e32 v207, v207, v251
	v_cvt_pk_bf16_f32 v172, v250, v251
	v_cvt_pk_bf16_f32 v173, v237, v196
	v_add_f32_e32 v197, v197, v237
	v_add_f32_e32 v207, v207, v196
	s_waitcnt lgkmcnt(3)
	v_mfma_f32_32x32x16_bf16 v[34:49], v[220:223], v[170:173], v[34:49]
	ds_read_b128 v[220:223], v163 offset:17472
	v_exp_f32_e32 v246, v98
	v_exp_f32_e32 v247, v99
	v_exp_f32_e32 v248, v100
	v_exp_f32_e32 v249, v101
	v_add_f32_e32 v197, v197, v246
	s_waitcnt lgkmcnt(3)
	v_mfma_f32_32x32x16_bf16 v[18:33], v[224:227], v[170:173], v[18:33]
	ds_read_b128 v[224:227], v163 offset:22080
	v_add_f32_e32 v207, v207, v247
	v_cvt_pk_bf16_f32 v242, v246, v247
	v_exp_f32_e32 v250, v102
	v_add_f32_e32 v197, v197, v248
	v_add_f32_e32 v207, v207, v249
	s_waitcnt lgkmcnt(3)
	v_mfma_f32_32x32x16_bf16 v[2:17], v[228:231], v[170:173], v[2:17]
	ds_read_b128 v[228:231], v163 offset:26688
	v_cvt_pk_bf16_f32 v243, v248, v249
	v_exp_f32_e32 v251, v103
	v_exp_f32_e32 v237, v104
	v_add_f32_e32 v197, v197, v250
	v_exp_f32_e32 v196, v105
	s_waitcnt lgkmcnt(3)
	v_mfma_f32_32x32x16_bf16 v[50:65], v[238:241], v[170:173], v[50:65]
	ds_read_b128 v[238:241], v163 offset:31296
	v_add_f32_e32 v207, v207, v251
	v_cvt_pk_bf16_f32 v244, v250, v251
	v_cvt_pk_bf16_f32 v245, v237, v196
	v_add_f32_e32 v197, v197, v237
	v_add_f32_e32 v207, v207, v196
	s_waitcnt lgkmcnt(3)
	v_mfma_f32_32x32x16_bf16 v[34:49], v[220:223], v[242:245], v[34:49]
	ds_read_b128 v[220:223], v163 offset:17504
	ds_read_b128 v[212:215], v206 offset:44544
	v_exp_f32_e32 v246, v106
	v_exp_f32_e32 v247, v107
	v_exp_f32_e32 v248, v108
	v_exp_f32_e32 v249, v109
	v_add_f32_e32 v197, v197, v246
	s_waitcnt lgkmcnt(4)
	v_mfma_f32_32x32x16_bf16 v[18:33], v[224:227], v[242:245], v[18:33]
	ds_read_b128 v[224:227], v163 offset:22112
	ds_read_b128 v[216:219], v206 offset:44576
	v_add_f32_e32 v207, v207, v247
	v_cvt_pk_bf16_f32 v170, v246, v247
	v_exp_f32_e32 v250, v110
	v_add_f32_e32 v197, v197, v248
	v_add_f32_e32 v207, v207, v249
	s_waitcnt lgkmcnt(5)
	v_mfma_f32_32x32x16_bf16 v[2:17], v[228:231], v[242:245], v[2:17]
	ds_read_b128 v[228:231], v163 offset:26720
	ds_read_b128 v[208:211], v206 offset:44608
	v_cvt_pk_bf16_f32 v171, v248, v249
	v_exp_f32_e32 v251, v111
	v_exp_f32_e32 v237, v112
	v_add_f32_e32 v197, v197, v250
	v_exp_f32_e32 v196, v113
	s_waitcnt lgkmcnt(6)
	v_mfma_f32_32x32x16_bf16 v[50:65], v[238:241], v[242:245], v[50:65]
	ds_read_b128 v[238:241], v163 offset:31328
	v_add_f32_e32 v207, v207, v251
	v_cvt_pk_bf16_f32 v172, v250, v251
	v_cvt_pk_bf16_f32 v173, v237, v196
	v_add_f32_e32 v197, v197, v237
	v_add_f32_e32 v207, v207, v196
	s_waitcnt lgkmcnt(5)
	v_mfma_f32_32x32x16_bf16 v[114:129], v[212:215], v[130:133], v[66:81]
	ds_read_b128 v[212:215], v206 offset:44640
	v_max3_f32 v246, v82, v83, v84
	s_waitcnt lgkmcnt(4)
	v_mfma_f32_32x32x16_bf16 v[114:129], v[216:219], v[134:137], v[114:129]
	v_max3_f32 v247, v85, v86, v87
	s_waitcnt lgkmcnt(2)
	v_mfma_f32_32x32x16_bf16 v[114:129], v[208:211], v[138:141], v[114:129]
	v_max3_f32 v246, v246, v88, v89
	s_waitcnt lgkmcnt(0)
	v_mfma_f32_32x32x16_bf16 v[114:129], v[212:215], v[142:145], v[114:129]
	v_max3_f32 v247, v247, v90, v91
	s_waitcnt lgkmcnt(0)
	s_barrier
	v_mfma_f32_32x32x16_bf16 v[34:49], v[220:223], v[170:173], v[34:49]
	ds_read_b128 v[220:223], v164 offset:0
	ds_read_b128 v[208:211], v162 offset:0
	v_max3_f32 v246, v246, v92, v93
	v_max3_f32 v247, v247, v94, v95
	v_mfma_f32_32x32x16_bf16 v[18:33], v[224:227], v[170:173], v[18:33]
	ds_read_b128 v[224:227], v164 offset:4608
	ds_read_b128 v[212:215], v162 offset:32
	v_max3_f32 v246, v246, v96, v97
	v_mfma_f32_32x32x16_bf16 v[2:17], v[228:231], v[170:173], v[2:17]
	ds_read_b128 v[228:231], v164 offset:9216
	ds_read_b128 v[216:219], v162 offset:64
	v_max3_f32 v247, v247, v114, v115
	v_max3_f32 v246, v246, v116, v117
	v_max3_f32 v247, v247, v118, v119
	v_max3_f32 v246, v246, v120, v121
	v_mfma_f32_32x32x16_bf16 v[50:65], v[238:241], v[170:173], v[50:65]
	ds_read_b128 v[238:241], v164 offset:13824
	v_max3_f32 v247, v247, v122, v123
	v_max3_f32 v246, v246, v124, v125
	v_max3_f32 v247, v247, v126, v127
	v_max3_f32 v246, v246, v128, v129
	v_max_f32_e32 v246, v246, v247
	v_mov_b32_e32 v247, v246
	s_nop 1
	v_permlane32_swap_b32_e32 v246, v247
	v_max_f32_e32 v246, v246, v247
	v_cmp_lt_f32_e32 vcc, 0x41000000, v246
	s_cbranch_vccnz .Lat_rare_0
.Lat_post_0:
	s_add_i32 s6, s6, 1
; #define MFMA32(a, b, c) __builtin_amdgcn_mfma_f32_32x32x16_bf16((a), (b), (c), 0, 0, 0)
; DI float ex2(float x) { return __builtin_amdgcn_exp2f(x); }
; #define A_LOAD(KB) { _Pragma("unroll") for (int i = 0; i < 2; ++i) { rk[i] = *(const u32x4*)(kp + (size_t)((KB) * 64 + 32 * i) * 1024); rv[i] = *(const u32x4*)(vp + (size_t)(64 * i) * TOK + (KB) * 64); } }
; DI void attn_block(const Params& p, int layer, int hd, int q0, int nkeys, char* smem) {
;     ...
;   for (int kb = 0; kb < nkb; ++kb) {
;     const char* Vs = smem + c0 * ST + KT;
;     A_STORE(c2);
;     A_LOAD((kb + 3 < lastkb) ? kb + 3 : lastkb);
;     if (kb + 1 < nkb) A_SCORES(sn, c1);
;     float mx = fmaxf(sc[0][0], sc[1][0]);
; #pragma unroll
;     for (int i = 1; i < 16; ++i) mx = fmaxf(mx, fmaxf(sc[0][i], sc[1][i]));
;     {
;       const auto pr_ = __builtin_amdgcn_permlane32_swap(__float_as_uint(mx), __float_as_uint(mx), false, false);
;       mx = fmaxf(__uint_as_float(pr_[0]), __uint_as_float(pr_[1]));
;     }
;     if (__any(mx > m + 8.f)) {
;       const float mn = (mx > m + 8.f) ? mx : m;
;       const float alpha = ex2(m - mn);
;       l *= alpha;
; #pragma unroll
;       for (int vt = 0; vt < 4; ++vt)
; #pragma unroll
;         for (int i = 0; i < 16; ++i) o[vt][i] *= alpha;
;       m = mn;
;     }
;     bf16x8 va[2][4];
;     const char* vbase = Vs + r * VROW + 16 * h;
; #pragma unroll
;     for (int vt = 0; vt < 4; ++vt) va[0][vt] = *(const bf16x8*)(vbase + 32 * vt * VROW);
;     float ls[4] = {0.f, 0.f, 0.f, 0.f};
; #pragma unroll
;     for (int st = 0; st < 4; ++st) {
;       if (st < 3) {
; #pragma unroll
;         for (int vt = 0; vt < 4; ++vt) va[(st + 1) & 1][vt] = *(const bf16x8*)(vbase + 32 * vt * VROW + (st + 1) * 32);
;       }
;       float pv[8];
; #pragma unroll
;       for (int i = 0; i < 8; ++i) { pv[i] = ex2(sc[st >> 1][8 * (st & 1) + i] - m); ls[i & 3] += pv[i]; }
;       u32x4 pk; pk.x = pack2(pv[0], pv[1]); pk.y = pack2(pv[2], pv[3]); pk.z = pack2(pv[4], pv[5]); pk.w = pack2(pv[6], pv[7]);
;       const bf16x8 pb = __builtin_bit_cast(bf16x8, pk);
; #pragma unroll
;       for (int vt = 0; vt < 4; ++vt) o[vt] = MFMA32(va[st & 1][vt], pb, o[vt]);
;     }
;     l += (ls[0] + ls[1]) + (ls[2] + ls[3]);
;     __syncthreads();
;     sc[0] = sn[0]; sc[1] = sn[1];
;     { const int tmp = c0; c0 = c1; c1 = c2; c2 = tmp; }
.Lat_top_1:
	s_waitcnt lgkmcnt(5)
	v_mfma_f32_32x32x16_bf16 v[98:113], v[208:211], v[130:133], v[66:81]
	ds_read_b128 v[208:211], v162 offset:96
	s_waitcnt vmcnt(0)
	ds_write_b128 v194, v[158:161] offset:16
	ds_write_b128 v194, v[154:157] offset:8720
	v_exp_f32_e32 v246, v82
	v_exp_f32_e32 v247, v83
	v_exp_f32_e32 v248, v84
	v_exp_f32_e32 v249, v85
	v_add_f32_e32 v197, v197, v246
	s_waitcnt lgkmcnt(6)
	v_mfma_f32_32x32x16_bf16 v[98:113], v[212:215], v[134:137], v[98:113]
	s_min_i32 s60, s6, 0x80
	s_add_i32 s60, s60, 3
	v_lshl_add_u32 v177, s60, 17, v175
	ds_write_b64 v205, v[146:147] offset:17424
	ds_write_b64 v205, v[148:149] offset:17440
	global_load_dwordx4 v[158:161], v177, s[52:53]
	global_load_dwordx4 v[154:157], v177, s[54:55]
	v_add_f32_e32 v207, v207, v247
	v_cvt_pk_bf16_f32 v242, v246, v247
	v_exp_f32_e32 v250, v86
	v_add_f32_e32 v197, v197, v248
	v_add_f32_e32 v207, v207, v249
	s_waitcnt lgkmcnt(6)
	v_mfma_f32_32x32x16_bf16 v[98:113], v[216:219], v[138:141], v[98:113]
	v_lshl_add_u32 v177, s60, 7, v176
	ds_write_b64 v205, v[150:151] offset:26640
	ds_write_b64 v205, v[152:153] offset:26656
	global_load_dwordx4 v[146:149], v177, s[56:57]
	global_load_dwordx4 v[150:153], v177, s[58:59]
	v_cvt_pk_bf16_f32 v243, v248, v249
	v_exp_f32_e32 v251, v87
	v_exp_f32_e32 v237, v88
	v_add_f32_e32 v197, v197, v250
	v_exp_f32_e32 v196, v89
	s_waitcnt lgkmcnt(6)
	v_mfma_f32_32x32x16_bf16 v[98:113], v[208:211], v[142:145], v[98:113]
	v_add_f32_e32 v207, v207, v251
	v_cvt_pk_bf16_f32 v244, v250, v251
	v_cvt_pk_bf16_f32 v245, v237, v196
	v_add_f32_e32 v197, v197, v237
	v_add_f32_e32 v207, v207, v196
	v_mfma_f32_32x32x16_bf16 v[34:49], v[220:223], v[242:245], v[34:49]
	ds_read_b128 v[220:223], v164 offset:32
	v_exp_f32_e32 v246, v90
	v_exp_f32_e32 v247, v91
	v_exp_f32_e32 v248, v92
	v_exp_f32_e32 v249, v93
	v_add_f32_e32 v197, v197, v246
	v_mfma_f32_32x32x16_bf16 v[18:33], v[224:227], v[242:245], v[18:33]
	ds_read_b128 v[224:227], v164 offset:4640
	v_add_f32_e32 v207, v207, v247
	v_cvt_pk_bf16_f32 v170, v246, v247
	v_exp_f32_e32 v250, v94
	v_add_f32_e32 v197, v197, v248
	v_add_f32_e32 v207, v207, v249
	v_mfma_f32_32x32x16_bf16 v[2:17], v[228:231], v[242:245], v[2:17]
	ds_read_b128 v[228:231], v164 offset:9248
	v_cvt_pk_bf16_f32 v171, v248, v249
	v_exp_f32_e32 v251, v95
	v_exp_f32_e32 v237, v96
	v_add_f32_e32 v197, v197, v250
	v_exp_f32_e32 v196, v97
	v_mfma_f32_32x32x16_bf16 v[50:65], v[238:241], v[242:245], v[50:65]
	ds_read_b128 v[238:241], v164 offset:13856
	v_add_f32_e32 v207, v207, v251
	v_cvt_pk_bf16_f32 v172, v250, v251
	v_cvt_pk_bf16_f32 v173, v237, v196
	v_add_f32_e32 v197, v197, v237
	v_add_f32_e32 v207, v207, v196
	s_waitcnt lgkmcnt(3)
	v_mfma_f32_32x32x16_bf16 v[34:49], v[220:223], v[170:173], v[34:49]
	ds_read_b128 v[220:223], v164 offset:64
	v_exp_f32_e32 v246, v114
	v_exp_f32_e32 v247, v115
	v_exp_f32_e32 v248, v116
	v_exp_f32_e32 v249, v117
	v_add_f32_e32 v197, v197, v246
	s_waitcnt lgkmcnt(3)
	v_mfma_f32_32x32x16_bf16 v[18:33], v[224:227], v[170:173], v[18:33]
	ds_read_b128 v[224:227], v164 offset:4672
	v_add_f32_e32 v207, v207, v247
	v_cvt_pk_bf16_f32 v242, v246, v247
	v_exp_f32_e32 v250, v118
	v_add_f32_e32 v197, v197, v248
	v_add_f32_e32 v207, v207, v249
	s_waitcnt lgkmcnt(3)
	v_mfma_f32_32x32x16_bf16 v[2:17], v[228:231], v[170:173], v[2:17]
	ds_read_b128 v[228:231], v164 offset:9280
	v_cvt_pk_bf16_f32 v243, v248, v249
	v_exp_f32_e32 v251, v119
	v_exp_f32_e32 v237, v120
	v_add_f32_e32 v197, v197, v250
	v_exp_f32_e32 v196, v121
	s_waitcnt lgkmcnt(3)
	v_mfma_f32_32x32x16_bf16 v[50:65], v[238:241], v[170:173], v[50:65]
	ds_read_b128 v[238:241], v164 offset:13888
	v_add_f32_e32 v207, v207, v251
	v_cvt_pk_bf16_f32 v244, v250, v251
	v_cvt_pk_bf16_f32 v245, v237, v196
	v_add_f32_e32 v197, v197, v237
	v_add_f32_e32 v207, v207, v196
	s_waitcnt lgkmcnt(3)
	v_mfma_f32_32x32x16_bf16 v[34:49], v[220:223], v[242:245], v[34:49]
	ds_read_b128 v[220:223], v164 offset:96
	ds_read_b128 v[212:215], v162 offset:8704
	v_exp_f32_e32 v246, v122
	v_exp_f32_e32 v247, v123
	v_exp_f32_e32 v248, v124
	v_exp_f32_e32 v249, v125
	v_add_f32_e32 v197, v197, v246
	s_waitcnt lgkmcnt(4)
	v_mfma_f32_32x32x16_bf16 v[18:33], v[224:227], v[242:245], v[18:33]
	ds_read_b128 v[224:227], v164 offset:4704
	ds_read_b128 v[216:219], v162 offset:8736
	v_add_f32_e32 v207, v207, v247
	v_cvt_pk_bf16_f32 v170, v246, v247
	v_exp_f32_e32 v250, v126
	v_add_f32_e32 v197, v197, v248
	v_add_f32_e32 v207, v207, v249
	s_waitcnt lgkmcnt(5)
	v_mfma_f32_32x32x16_bf16 v[2:17], v[228:231], v[242:245], v[2:17]
	ds_read_b128 v[228:231], v164 offset:9312
	ds_read_b128 v[208:211], v162 offset:8768
	v_cvt_pk_bf16_f32 v171, v248, v249
	v_exp_f32_e32 v251, v127
	v_exp_f32_e32 v237, v128
	v_add_f32_e32 v197, v197, v250
	v_exp_f32_e32 v196, v129
	s_waitcnt lgkmcnt(6)
	v_mfma_f32_32x32x16_bf16 v[50:65], v[238:241], v[242:245], v[50:65]
	ds_read_b128 v[238:241], v164 offset:13920
	v_add_f32_e32 v207, v207, v251
	v_cvt_pk_bf16_f32 v172, v250, v251
	v_cvt_pk_bf16_f32 v173, v237, v196
	v_add_f32_e32 v197, v197, v237
	v_add_f32_e32 v207, v207, v196
	s_waitcnt lgkmcnt(5)
	v_mfma_f32_32x32x16_bf16 v[82:97], v[212:215], v[130:133], v[66:81]
	ds_read_b128 v[212:215], v162 offset:8800
	v_max3_f32 v246, v98, v99, v100
	s_waitcnt lgkmcnt(4)
	v_mfma_f32_32x32x16_bf16 v[82:97], v[216:219], v[134:137], v[82:97]
	v_max3_f32 v247, v101, v102, v103
	s_waitcnt lgkmcnt(2)
	v_mfma_f32_32x32x16_bf16 v[82:97], v[208:211], v[138:141], v[82:97]
	v_max3_f32 v246, v246, v104, v105
	s_waitcnt lgkmcnt(0)
	v_mfma_f32_32x32x16_bf16 v[82:97], v[212:215], v[142:145], v[82:97]
	v_max3_f32 v247, v247, v106, v107
	s_waitcnt lgkmcnt(0)
	s_barrier
	v_mfma_f32_32x32x16_bf16 v[34:49], v[220:223], v[170:173], v[34:49]
	ds_read_b128 v[220:223], v164 offset:35840
	ds_read_b128 v[208:211], v206 offset:0
	v_max3_f32 v246, v246, v108, v109
	v_max3_f32 v247, v247, v110, v111
	v_mfma_f32_32x32x16_bf16 v[18:33], v[224:227], v[170:173], v[18:33]
	ds_read_b128 v[224:227], v164 offset:40448
	ds_read_b128 v[212:215], v206 offset:32
	v_max3_f32 v246, v246, v112, v113
	v_mfma_f32_32x32x16_bf16 v[2:17], v[228:231], v[170:173], v[2:17]
	ds_read_b128 v[228:231], v164 offset:45056
	ds_read_b128 v[216:219], v206 offset:64
	v_max3_f32 v247, v247, v82, v83
	v_max3_f32 v246, v246, v84, v85
	v_max3_f32 v247, v247, v86, v87
	v_max3_f32 v246, v246, v88, v89
	v_mfma_f32_32x32x16_bf16 v[50:65], v[238:241], v[170:173], v[50:65]
	ds_read_b128 v[238:241], v164 offset:49664
	v_max3_f32 v247, v247, v90, v91
	v_max3_f32 v246, v246, v92, v93
	v_max3_f32 v247, v247, v94, v95
	v_max3_f32 v246, v246, v96, v97
	v_max_f32_e32 v246, v246, v247
	v_mov_b32_e32 v247, v246
	s_nop 1
	v_permlane32_swap_b32_e32 v246, v247
	v_max_f32_e32 v246, v246, v247
	v_cmp_lt_f32_e32 vcc, 0x41000000, v246
	s_cbranch_vccnz .Lat_rare_1
; #define MFMA32(a, b, c) __builtin_amdgcn_mfma_f32_32x32x16_bf16((a), (b), (c), 0, 0, 0)
; DI float ex2(float x) { return __builtin_amdgcn_exp2f(x); }
; #define A_LOAD(KB) { _Pragma("unroll") for (int i = 0; i < 2; ++i) { rk[i] = *(const u32x4*)(kp + (size_t)((KB) * 64 + 32 * i) * 1024); rv[i] = *(const u32x4*)(vp + (size_t)(64 * i) * TOK + (KB) * 64); } }
; DI void attn_block(const Params& p, int layer, int hd, int q0, int nkeys, char* smem) {
;     ...
;   for (int kb = 0; kb < nkb; ++kb) {
;     const char* Vs = smem + c0 * ST + KT;
;     A_STORE(c2);
;     A_LOAD((kb + 3 < lastkb) ? kb + 3 : lastkb);
;     if (kb + 1 < nkb) A_SCORES(sn, c1);
;     float mx = fmaxf(sc[0][0], sc[1][0]);
; #pragma unroll
;     for (int i = 1; i < 16; ++i) mx = fmaxf(mx, fmaxf(sc[0][i], sc[1][i]));
;     {
;       const auto pr_ = __builtin_amdgcn_permlane32_swap(__float_as_uint(mx), __float_as_uint(mx), false, false);
;       mx = fmaxf(__uint_as_float(pr_[0]), __uint_as_float(pr_[1]));
;     }
;     if (__any(mx > m + 8.f)) {
;       const float mn = (mx > m + 8.f) ? mx : m;
;       const float alpha = ex2(m - mn);
;       l *= alpha;
; #pragma unroll
;       for (int vt = 0; vt < 4; ++vt)
; #pragma unroll
;         for (int i = 0; i < 16; ++i) o[vt][i] *= alpha;
;       m = mn;
;     }
;     bf16x8 va[2][4];
;     const char* vbase = Vs + r * VROW + 16 * h;
; #pragma unroll
;     for (int vt = 0; vt < 4; ++vt) va[0][vt] = *(const bf16x8*)(vbase + 32 * vt * VROW);
;     float ls[4] = {0.f, 0.f, 0.f, 0.f};
; #pragma unroll
;     for (int st = 0; st < 4; ++st) {
;       if (st < 3) {
; #pragma unroll
;         for (int vt = 0; vt < 4; ++vt) va[(st + 1) & 1][vt] = *(const bf16x8*)(vbase + 32 * vt * VROW + (st + 1) * 32);
;       }
;       float pv[8];
; #pragma unroll
;       for (int i = 0; i < 8; ++i) { pv[i] = ex2(sc[st >> 1][8 * (st & 1) + i] - m); ls[i & 3] += pv[i]; }
;       u32x4 pk; pk.x = pack2(pv[0], pv[1]); pk.y = pack2(pv[2], pv[3]); pk.z = pack2(pv[4], pv[5]); pk.w = pack2(pv[6], pv[7]);
;       const bf16x8 pb = __builtin_bit_cast(bf16x8, pk);
; #pragma unroll
;       for (int vt = 0; vt < 4; ++vt) o[vt] = MFMA32(va[st & 1][vt], pb, o[vt]);
;     }
;     l += (ls[0] + ls[1]) + (ls[2] + ls[3]);
;     __syncthreads();
;     sc[0] = sn[0]; sc[1] = sn[1];
;     { const int tmp = c0; c0 = c1; c1 = c2; c2 = tmp; }
.Lat_post_1:
	s_add_i32 s6, s6, 1
	s_cmpk_eq_i32 s6, 0x83
	s_cbranch_scc1 .Lat_exit
.Lat_top_2:
	s_waitcnt lgkmcnt(5)
	v_mfma_f32_32x32x16_bf16 v[114:129], v[208:211], v[130:133], v[66:81]
	ds_read_b128 v[208:211], v206 offset:96
	s_waitcnt vmcnt(0)
	ds_write_b128 v194, v[158:161] offset:35856
	ds_write_b128 v194, v[154:157] offset:44560
	v_exp_f32_e32 v246, v98
	v_exp_f32_e32 v247, v99
	v_exp_f32_e32 v248, v100
	v_exp_f32_e32 v249, v101
	v_add_f32_e32 v197, v197, v246
	s_waitcnt lgkmcnt(6)
	v_mfma_f32_32x32x16_bf16 v[114:129], v[212:215], v[134:137], v[114:129]
	s_min_i32 s60, s6, 0x80
	s_add_i32 s60, s60, 3
	v_lshl_add_u32 v177, s60, 17, v175
	ds_write_b64 v205, v[146:147] offset:53264
	ds_write_b64 v205, v[148:149] offset:53280
	global_load_dwordx4 v[158:161], v177, s[52:53]
	global_load_dwordx4 v[154:157], v177, s[54:55]
	v_add_f32_e32 v207, v207, v247
	v_cvt_pk_bf16_f32 v242, v246, v247
	v_exp_f32_e32 v250, v102
	v_add_f32_e32 v197, v197, v248
	v_add_f32_e32 v207, v207, v249
	s_waitcnt lgkmcnt(6)
	v_mfma_f32_32x32x16_bf16 v[114:129], v[216:219], v[138:141], v[114:129]
	v_lshl_add_u32 v177, s60, 7, v176
	ds_write_b64 v205, v[150:151] offset:62480
	ds_write_b64 v205, v[152:153] offset:62496
	global_load_dwordx4 v[146:149], v177, s[56:57]
	global_load_dwordx4 v[150:153], v177, s[58:59]
	v_cvt_pk_bf16_f32 v243, v248, v249
	v_exp_f32_e32 v251, v103
	v_exp_f32_e32 v237, v104
	v_add_f32_e32 v197, v197, v250
	v_exp_f32_e32 v196, v105
	s_waitcnt lgkmcnt(6)
	v_mfma_f32_32x32x16_bf16 v[114:129], v[208:211], v[142:145], v[114:129]
	v_add_f32_e32 v207, v207, v251
	v_cvt_pk_bf16_f32 v244, v250, v251
	v_cvt_pk_bf16_f32 v245, v237, v196
	v_add_f32_e32 v197, v197, v237
	v_add_f32_e32 v207, v207, v196
	v_mfma_f32_32x32x16_bf16 v[34:49], v[220:223], v[242:245], v[34:49]
	ds_read_b128 v[220:223], v164 offset:35872
	v_exp_f32_e32 v246, v106
	v_exp_f32_e32 v247, v107
	v_exp_f32_e32 v248, v108
	v_exp_f32_e32 v249, v109
	v_add_f32_e32 v197, v197, v246
	v_mfma_f32_32x32x16_bf16 v[18:33], v[224:227], v[242:245], v[18:33]
	ds_read_b128 v[224:227], v164 offset:40480
	v_add_f32_e32 v207, v207, v247
	v_cvt_pk_bf16_f32 v170, v246, v247
	v_exp_f32_e32 v250, v110
	v_add_f32_e32 v197, v197, v248
	v_add_f32_e32 v207, v207, v249
	v_mfma_f32_32x32x16_bf16 v[2:17], v[228:231], v[242:245], v[2:17]
	ds_read_b128 v[228:231], v164 offset:45088
	v_cvt_pk_bf16_f32 v171, v248, v249
	v_exp_f32_e32 v251, v111
	v_exp_f32_e32 v237, v112
	v_add_f32_e32 v197, v197, v250
	v_exp_f32_e32 v196, v113
	v_mfma_f32_32x32x16_bf16 v[50:65], v[238:241], v[242:245], v[50:65]
	ds_read_b128 v[238:241], v164 offset:49696
	v_add_f32_e32 v207, v207, v251
	v_cvt_pk_bf16_f32 v172, v250, v251
	v_cvt_pk_bf16_f32 v173, v237, v196
	v_add_f32_e32 v197, v197, v237
	v_add_f32_e32 v207, v207, v196
	s_waitcnt lgkmcnt(3)
	v_mfma_f32_32x32x16_bf16 v[34:49], v[220:223], v[170:173], v[34:49]
	ds_read_b128 v[220:223], v164 offset:35904
	v_exp_f32_e32 v246, v82
	v_exp_f32_e32 v247, v83
	v_exp_f32_e32 v248, v84
	v_exp_f32_e32 v249, v85
	v_add_f32_e32 v197, v197, v246
	s_waitcnt lgkmcnt(3)
	v_mfma_f32_32x32x16_bf16 v[18:33], v[224:227], v[170:173], v[18:33]
	ds_read_b128 v[224:227], v164 offset:40512
	v_add_f32_e32 v207, v207, v247
	v_cvt_pk_bf16_f32 v242, v246, v247
	v_exp_f32_e32 v250, v86
	v_add_f32_e32 v197, v197, v248
	v_add_f32_e32 v207, v207, v249
	s_waitcnt lgkmcnt(3)
	v_mfma_f32_32x32x16_bf16 v[2:17], v[228:231], v[170:173], v[2:17]
	ds_read_b128 v[228:231], v164 offset:45120
	v_cvt_pk_bf16_f32 v243, v248, v249
	v_exp_f32_e32 v251, v87
	v_exp_f32_e32 v237, v88
	v_add_f32_e32 v197, v197, v250
	v_exp_f32_e32 v196, v89
	s_waitcnt lgkmcnt(3)
	v_mfma_f32_32x32x16_bf16 v[50:65], v[238:241], v[170:173], v[50:65]
	ds_read_b128 v[238:241], v164 offset:49728
	v_add_f32_e32 v207, v207, v251
	v_cvt_pk_bf16_f32 v244, v250, v251
	v_cvt_pk_bf16_f32 v245, v237, v196
	v_add_f32_e32 v197, v197, v237
	v_add_f32_e32 v207, v207, v196
	s_waitcnt lgkmcnt(3)
	v_mfma_f32_32x32x16_bf16 v[34:49], v[220:223], v[242:245], v[34:49]
	ds_read_b128 v[220:223], v164 offset:35936
	ds_read_b128 v[212:215], v206 offset:8704
	v_exp_f32_e32 v246, v90
	v_exp_f32_e32 v247, v91
	v_exp_f32_e32 v248, v92
	v_exp_f32_e32 v249, v93
	v_add_f32_e32 v197, v197, v246
	s_waitcnt lgkmcnt(4)
	v_mfma_f32_32x32x16_bf16 v[18:33], v[224:227], v[242:245], v[18:33]
	ds_read_b128 v[224:227], v164 offset:40544
	ds_read_b128 v[216:219], v206 offset:8736
	v_add_f32_e32 v207, v207, v247
	v_cvt_pk_bf16_f32 v170, v246, v247
	v_exp_f32_e32 v250, v94
	v_add_f32_e32 v197, v197, v248
	v_add_f32_e32 v207, v207, v249
	s_waitcnt lgkmcnt(5)
	v_mfma_f32_32x32x16_bf16 v[2:17], v[228:231], v[242:245], v[2:17]
	ds_read_b128 v[228:231], v164 offset:45152
	ds_read_b128 v[208:211], v206 offset:8768
	v_cvt_pk_bf16_f32 v171, v248, v249
	v_exp_f32_e32 v251, v95
	v_exp_f32_e32 v237, v96
	v_add_f32_e32 v197, v197, v250
	v_exp_f32_e32 v196, v97
	s_waitcnt lgkmcnt(6)
	v_mfma_f32_32x32x16_bf16 v[50:65], v[238:241], v[242:245], v[50:65]
	ds_read_b128 v[238:241], v164 offset:49760
	v_add_f32_e32 v207, v207, v251
	v_cvt_pk_bf16_f32 v172, v250, v251
	v_cvt_pk_bf16_f32 v173, v237, v196
	v_add_f32_e32 v197, v197, v237
	v_add_f32_e32 v207, v207, v196
	s_waitcnt lgkmcnt(5)
	v_mfma_f32_32x32x16_bf16 v[98:113], v[212:215], v[130:133], v[66:81]
	ds_read_b128 v[212:215], v206 offset:8800
	v_max3_f32 v246, v114, v115, v116
	s_waitcnt lgkmcnt(4)
	v_mfma_f32_32x32x16_bf16 v[98:113], v[216:219], v[134:137], v[98:113]
	v_max3_f32 v247, v117, v118, v119
	s_waitcnt lgkmcnt(2)
	v_mfma_f32_32x32x16_bf16 v[98:113], v[208:211], v[138:141], v[98:113]
	v_max3_f32 v246, v246, v120, v121
	s_waitcnt lgkmcnt(0)
	v_mfma_f32_32x32x16_bf16 v[98:113], v[212:215], v[142:145], v[98:113]
	v_max3_f32 v247, v247, v122, v123
	s_waitcnt lgkmcnt(0)
	s_barrier
	v_mfma_f32_32x32x16_bf16 v[34:49], v[220:223], v[170:173], v[34:49]
	ds_read_b128 v[220:223], v163 offset:17408
	ds_read_b128 v[208:211], v206 offset:35840
	v_max3_f32 v246, v246, v124, v125
	v_max3_f32 v247, v247, v126, v127
	v_mfma_f32_32x32x16_bf16 v[18:33], v[224:227], v[170:173], v[18:33]
	ds_read_b128 v[224:227], v163 offset:22016
	ds_read_b128 v[212:215], v206 offset:35872
	v_max3_f32 v246, v246, v128, v129
	v_mfma_f32_32x32x16_bf16 v[2:17], v[228:231], v[170:173], v[2:17]
	ds_read_b128 v[228:231], v163 offset:26624
	ds_read_b128 v[216:219], v206 offset:35904
	v_max3_f32 v247, v247, v98, v99
	v_max3_f32 v246, v246, v100, v101
	v_max3_f32 v247, v247, v102, v103
	v_max3_f32 v246, v246, v104, v105
	v_mfma_f32_32x32x16_bf16 v[50:65], v[238:241], v[170:173], v[50:65]
	ds_read_b128 v[238:241], v163 offset:31232
	v_max3_f32 v247, v247, v106, v107
	v_max3_f32 v246, v246, v108, v109
	v_max3_f32 v247, v247, v110, v111
	v_max3_f32 v246, v246, v112, v113
	v_max_f32_e32 v246, v246, v247
	v_mov_b32_e32 v247, v246
	s_nop 1
	v_permlane32_swap_b32_e32 v246, v247
	v_max_f32_e32 v246, v246, v247
	v_cmp_lt_f32_e32 vcc, 0x41000000, v246
	s_cbranch_vccnz .Lat_rare_2
; DI float ex2(float x) { return __builtin_amdgcn_exp2f(x); }
; DI void attn_block(const Params& p, int layer, int hd, int q0, int nkeys, char* smem) {
;     ...
;     if (__any(mx > m + 8.f)) {
;       const float mn = (mx > m + 8.f) ? mx : m;
;       const float alpha = ex2(m - mn);
;       l *= alpha;
; #pragma unroll
;       for (int vt = 0; vt < 4; ++vt)
; #pragma unroll
;         for (int i = 0; i < 16; ++i) o[vt][i] *= alpha;
;       m = mn;
;     }
.Lat_post_2:
	s_add_i32 s6, s6, 1
	s_branch .Lat_top_0
.Lat_rare_0:
	s_nop 1
	v_cndmask_b32_e32 v247, 0, v246, vcc
	v_sub_f32_e32 v66, v66, v247
	v_exp_f32_e64 v248, -v247
	v_sub_f32_e32 v82, v82, v247
	v_sub_f32_e32 v83, v83, v247
	v_sub_f32_e32 v84, v84, v247
	v_sub_f32_e32 v85, v85, v247
	v_sub_f32_e32 v86, v86, v247
	v_sub_f32_e32 v87, v87, v247
	v_sub_f32_e32 v88, v88, v247
	v_sub_f32_e32 v89, v89, v247
	v_sub_f32_e32 v90, v90, v247
	v_sub_f32_e32 v91, v91, v247
	v_sub_f32_e32 v92, v92, v247
	v_sub_f32_e32 v93, v93, v247
	v_sub_f32_e32 v94, v94, v247
	v_sub_f32_e32 v95, v95, v247
	v_sub_f32_e32 v96, v96, v247
	v_sub_f32_e32 v97, v97, v247
	v_sub_f32_e32 v114, v114, v247
	v_sub_f32_e32 v115, v115, v247
	v_sub_f32_e32 v116, v116, v247
	v_sub_f32_e32 v117, v117, v247
	v_sub_f32_e32 v118, v118, v247
	v_sub_f32_e32 v119, v119, v247
	v_sub_f32_e32 v120, v120, v247
	v_sub_f32_e32 v121, v121, v247
	v_sub_f32_e32 v122, v122, v247
	v_sub_f32_e32 v123, v123, v247
	v_sub_f32_e32 v124, v124, v247
	v_sub_f32_e32 v125, v125, v247
	v_sub_f32_e32 v126, v126, v247
	v_sub_f32_e32 v127, v127, v247
	v_sub_f32_e32 v128, v128, v247
	v_sub_f32_e32 v129, v129, v247
	v_mov_b32_e32 v67, v66
	v_mov_b32_e32 v68, v66
	v_mov_b32_e32 v69, v66
	v_mov_b32_e32 v70, v66
	v_mov_b32_e32 v71, v66
	v_mov_b32_e32 v72, v66
	v_mov_b32_e32 v73, v66
	v_mov_b32_e32 v74, v66
	v_mov_b32_e32 v75, v66
	v_mov_b32_e32 v76, v66
	v_mov_b32_e32 v77, v66
	v_mov_b32_e32 v78, v66
	v_mov_b32_e32 v79, v66
	v_mov_b32_e32 v80, v66
	v_mov_b32_e32 v81, v66
	v_mul_f32_e32 v197, v197, v248
	v_mul_f32_e32 v207, v207, v248
	v_mul_f32_e32 v34, v34, v248
	v_mul_f32_e32 v35, v35, v248
	v_mul_f32_e32 v36, v36, v248
	v_mul_f32_e32 v37, v37, v248
	v_mul_f32_e32 v38, v38, v248
	v_mul_f32_e32 v39, v39, v248
	v_mul_f32_e32 v40, v40, v248
	v_mul_f32_e32 v41, v41, v248
	v_mul_f32_e32 v42, v42, v248
	v_mul_f32_e32 v43, v43, v248
	v_mul_f32_e32 v44, v44, v248
	v_mul_f32_e32 v45, v45, v248
	v_mul_f32_e32 v46, v46, v248
	v_mul_f32_e32 v47, v47, v248
	v_mul_f32_e32 v48, v48, v248
	v_mul_f32_e32 v49, v49, v248
	v_mul_f32_e32 v18, v18, v248
	v_mul_f32_e32 v19, v19, v248
	v_mul_f32_e32 v20, v20, v248
	v_mul_f32_e32 v21, v21, v248
	v_mul_f32_e32 v22, v22, v248
	v_mul_f32_e32 v23, v23, v248
	v_mul_f32_e32 v24, v24, v248
	v_mul_f32_e32 v25, v25, v248
	v_mul_f32_e32 v26, v26, v248
	v_mul_f32_e32 v27, v27, v248
	v_mul_f32_e32 v28, v28, v248
	v_mul_f32_e32 v29, v29, v248
	v_mul_f32_e32 v30, v30, v248
	v_mul_f32_e32 v31, v31, v248
	v_mul_f32_e32 v32, v32, v248
	v_mul_f32_e32 v33, v33, v248
	v_mul_f32_e32 v2, v2, v248
	v_mul_f32_e32 v3, v3, v248
	v_mul_f32_e32 v4, v4, v248
	v_mul_f32_e32 v5, v5, v248
	v_mul_f32_e32 v6, v6, v248
	v_mul_f32_e32 v7, v7, v248
	v_mul_f32_e32 v8, v8, v248
	v_mul_f32_e32 v9, v9, v248
	v_mul_f32_e32 v10, v10, v248
	v_mul_f32_e32 v11, v11, v248
	v_mul_f32_e32 v12, v12, v248
	v_mul_f32_e32 v13, v13, v248
	v_mul_f32_e32 v14, v14, v248
	v_mul_f32_e32 v15, v15, v248
	v_mul_f32_e32 v16, v16, v248
	v_mul_f32_e32 v17, v17, v248
	v_mul_f32_e32 v50, v50, v248
	v_mul_f32_e32 v51, v51, v248
	v_mul_f32_e32 v52, v52, v248
	v_mul_f32_e32 v53, v53, v248
	v_mul_f32_e32 v54, v54, v248
	v_mul_f32_e32 v55, v55, v248
	v_mul_f32_e32 v56, v56, v248
	v_mul_f32_e32 v57, v57, v248
	v_mul_f32_e32 v58, v58, v248
	v_mul_f32_e32 v59, v59, v248
	v_mul_f32_e32 v60, v60, v248
	v_mul_f32_e32 v61, v61, v248
	v_mul_f32_e32 v62, v62, v248
	v_mul_f32_e32 v63, v63, v248
	v_mul_f32_e32 v64, v64, v248
	v_mul_f32_e32 v65, v65, v248
	s_branch .Lat_post_0
.Lat_rare_1:
	s_nop 1
	v_cndmask_b32_e32 v247, 0, v246, vcc
	v_sub_f32_e32 v66, v66, v247
	v_exp_f32_e64 v248, -v247
	v_sub_f32_e32 v98, v98, v247
	v_sub_f32_e32 v99, v99, v247
	v_sub_f32_e32 v100, v100, v247
	v_sub_f32_e32 v101, v101, v247
	v_sub_f32_e32 v102, v102, v247
	v_sub_f32_e32 v103, v103, v247
	v_sub_f32_e32 v104, v104, v247
	v_sub_f32_e32 v105, v105, v247
	v_sub_f32_e32 v106, v106, v247
	v_sub_f32_e32 v107, v107, v247
	v_sub_f32_e32 v108, v108, v247
	v_sub_f32_e32 v109, v109, v247
	v_sub_f32_e32 v110, v110, v247
	v_sub_f32_e32 v111, v111, v247
	v_sub_f32_e32 v112, v112, v247
	v_sub_f32_e32 v113, v113, v247
	v_sub_f32_e32 v82, v82, v247
	v_sub_f32_e32 v83, v83, v247
	v_sub_f32_e32 v84, v84, v247
	v_sub_f32_e32 v85, v85, v247
	v_sub_f32_e32 v86, v86, v247
	v_sub_f32_e32 v87, v87, v247
	v_sub_f32_e32 v88, v88, v247
	v_sub_f32_e32 v89, v89, v247
	v_sub_f32_e32 v90, v90, v247
	v_sub_f32_e32 v91, v91, v247
	v_sub_f32_e32 v92, v92, v247
	v_sub_f32_e32 v93, v93, v247
	v_sub_f32_e32 v94, v94, v247
	v_sub_f32_e32 v95, v95, v247
	v_sub_f32_e32 v96, v96, v247
	v_sub_f32_e32 v97, v97, v247
	v_mov_b32_e32 v67, v66
	v_mov_b32_e32 v68, v66
	v_mov_b32_e32 v69, v66
	v_mov_b32_e32 v70, v66
	v_mov_b32_e32 v71, v66
	v_mov_b32_e32 v72, v66
	v_mov_b32_e32 v73, v66
	v_mov_b32_e32 v74, v66
	v_mov_b32_e32 v75, v66
	v_mov_b32_e32 v76, v66
	v_mov_b32_e32 v77, v66
	v_mov_b32_e32 v78, v66
	v_mov_b32_e32 v79, v66
	v_mov_b32_e32 v80, v66
	v_mov_b32_e32 v81, v66
	v_mul_f32_e32 v197, v197, v248
	v_mul_f32_e32 v207, v207, v248
	v_mul_f32_e32 v34, v34, v248
	v_mul_f32_e32 v35, v35, v248
	v_mul_f32_e32 v36, v36, v248
	v_mul_f32_e32 v37, v37, v248
	v_mul_f32_e32 v38, v38, v248
	v_mul_f32_e32 v39, v39, v248
	v_mul_f32_e32 v40, v40, v248
	v_mul_f32_e32 v41, v41, v248
	v_mul_f32_e32 v42, v42, v248
	v_mul_f32_e32 v43, v43, v248
	v_mul_f32_e32 v44, v44, v248
	v_mul_f32_e32 v45, v45, v248
	v_mul_f32_e32 v46, v46, v248
	v_mul_f32_e32 v47, v47, v248
	v_mul_f32_e32 v48, v48, v248
	v_mul_f32_e32 v49, v49, v248
	v_mul_f32_e32 v18, v18, v248
	v_mul_f32_e32 v19, v19, v248
	v_mul_f32_e32 v20, v20, v248
	v_mul_f32_e32 v21, v21, v248
	v_mul_f32_e32 v22, v22, v248
	v_mul_f32_e32 v23, v23, v248
	v_mul_f32_e32 v24, v24, v248
	v_mul_f32_e32 v25, v25, v248
	v_mul_f32_e32 v26, v26, v248
	v_mul_f32_e32 v27, v27, v248
	v_mul_f32_e32 v28, v28, v248
	v_mul_f32_e32 v29, v29, v248
	v_mul_f32_e32 v30, v30, v248
	v_mul_f32_e32 v31, v31, v248
	v_mul_f32_e32 v32, v32, v248
	v_mul_f32_e32 v33, v33, v248
	v_mul_f32_e32 v2, v2, v248
	v_mul_f32_e32 v3, v3, v248
	v_mul_f32_e32 v4, v4, v248
	v_mul_f32_e32 v5, v5, v248
	v_mul_f32_e32 v6, v6, v248
	v_mul_f32_e32 v7, v7, v248
	v_mul_f32_e32 v8, v8, v248
	v_mul_f32_e32 v9, v9, v248
	v_mul_f32_e32 v10, v10, v248
	v_mul_f32_e32 v11, v11, v248
	v_mul_f32_e32 v12, v12, v248
	v_mul_f32_e32 v13, v13, v248
	v_mul_f32_e32 v14, v14, v248
	v_mul_f32_e32 v15, v15, v248
	v_mul_f32_e32 v16, v16, v248
	v_mul_f32_e32 v17, v17, v248
	v_mul_f32_e32 v50, v50, v248
	v_mul_f32_e32 v51, v51, v248
	v_mul_f32_e32 v52, v52, v248
	v_mul_f32_e32 v53, v53, v248
	v_mul_f32_e32 v54, v54, v248
	v_mul_f32_e32 v55, v55, v248
	v_mul_f32_e32 v56, v56, v248
	v_mul_f32_e32 v57, v57, v248
	v_mul_f32_e32 v58, v58, v248
	v_mul_f32_e32 v59, v59, v248
	v_mul_f32_e32 v60, v60, v248
	v_mul_f32_e32 v61, v61, v248
	v_mul_f32_e32 v62, v62, v248
	v_mul_f32_e32 v63, v63, v248
	v_mul_f32_e32 v64, v64, v248
	v_mul_f32_e32 v65, v65, v248
	s_branch .Lat_post_1
; DI float ex2(float x) { return __builtin_amdgcn_exp2f(x); }
; DI void attn_block(const Params& p, int layer, int hd, int q0, int nkeys, char* smem) {
;     ...
;     if (__any(mx > m + 8.f)) {
;       const float mn = (mx > m + 8.f) ? mx : m;
;       const float alpha = ex2(m - mn);
;       l *= alpha;
; #pragma unroll
;       for (int vt = 0; vt < 4; ++vt)
; #pragma unroll
;         for (int i = 0; i < 16; ++i) o[vt][i] *= alpha;
;       m = mn;
;     }
;     ...
;     l += (ls[0] + ls[1]) + (ls[2] + ls[3]);
;     __syncthreads();
;     sc[0] = sn[0]; sc[1] = sn[1];
;     { const int tmp = c0; c0 = c1; c1 = c2; c2 = tmp; }
;   }
;     ...
;   l += __shfl_xor(l, 32);
;   const float scl = (mp == 0 ? 1.f : scal[16 + layer]) / l;
.Lat_rare_2:
	s_nop 1
	v_cndmask_b32_e32 v247, 0, v246, vcc
	v_sub_f32_e32 v66, v66, v247
	v_exp_f32_e64 v248, -v247
	v_sub_f32_e32 v114, v114, v247
	v_sub_f32_e32 v115, v115, v247
	v_sub_f32_e32 v116, v116, v247
	v_sub_f32_e32 v117, v117, v247
	v_sub_f32_e32 v118, v118, v247
	v_sub_f32_e32 v119, v119, v247
	v_sub_f32_e32 v120, v120, v247
	v_sub_f32_e32 v121, v121, v247
	v_sub_f32_e32 v122, v122, v247
	v_sub_f32_e32 v123, v123, v247
	v_sub_f32_e32 v124, v124, v247
	v_sub_f32_e32 v125, v125, v247
	v_sub_f32_e32 v126, v126, v247
	v_sub_f32_e32 v127, v127, v247
	v_sub_f32_e32 v128, v128, v247
	v_sub_f32_e32 v129, v129, v247
	v_sub_f32_e32 v98, v98, v247
	v_sub_f32_e32 v99, v99, v247
	v_sub_f32_e32 v100, v100, v247
	v_sub_f32_e32 v101, v101, v247
	v_sub_f32_e32 v102, v102, v247
	v_sub_f32_e32 v103, v103, v247
	v_sub_f32_e32 v104, v104, v247
	v_sub_f32_e32 v105, v105, v247
	v_sub_f32_e32 v106, v106, v247
	v_sub_f32_e32 v107, v107, v247
	v_sub_f32_e32 v108, v108, v247
	v_sub_f32_e32 v109, v109, v247
	v_sub_f32_e32 v110, v110, v247
	v_sub_f32_e32 v111, v111, v247
	v_sub_f32_e32 v112, v112, v247
	v_sub_f32_e32 v113, v113, v247
	v_mov_b32_e32 v67, v66
	v_mov_b32_e32 v68, v66
	v_mov_b32_e32 v69, v66
	v_mov_b32_e32 v70, v66
	v_mov_b32_e32 v71, v66
	v_mov_b32_e32 v72, v66
	v_mov_b32_e32 v73, v66
	v_mov_b32_e32 v74, v66
	v_mov_b32_e32 v75, v66
	v_mov_b32_e32 v76, v66
	v_mov_b32_e32 v77, v66
	v_mov_b32_e32 v78, v66
	v_mov_b32_e32 v79, v66
	v_mov_b32_e32 v80, v66
	v_mov_b32_e32 v81, v66
	v_mul_f32_e32 v197, v197, v248
	v_mul_f32_e32 v207, v207, v248
	v_mul_f32_e32 v34, v34, v248
	v_mul_f32_e32 v35, v35, v248
	v_mul_f32_e32 v36, v36, v248
	v_mul_f32_e32 v37, v37, v248
	v_mul_f32_e32 v38, v38, v248
	v_mul_f32_e32 v39, v39, v248
	v_mul_f32_e32 v40, v40, v248
	v_mul_f32_e32 v41, v41, v248
	v_mul_f32_e32 v42, v42, v248
	v_mul_f32_e32 v43, v43, v248
	v_mul_f32_e32 v44, v44, v248
	v_mul_f32_e32 v45, v45, v248
	v_mul_f32_e32 v46, v46, v248
	v_mul_f32_e32 v47, v47, v248
	v_mul_f32_e32 v48, v48, v248
	v_mul_f32_e32 v49, v49, v248
	v_mul_f32_e32 v18, v18, v248
	v_mul_f32_e32 v19, v19, v248
	v_mul_f32_e32 v20, v20, v248
	v_mul_f32_e32 v21, v21, v248
	v_mul_f32_e32 v22, v22, v248
	v_mul_f32_e32 v23, v23, v248
	v_mul_f32_e32 v24, v24, v248
	v_mul_f32_e32 v25, v25, v248
	v_mul_f32_e32 v26, v26, v248
	v_mul_f32_e32 v27, v27, v248
	v_mul_f32_e32 v28, v28, v248
	v_mul_f32_e32 v29, v29, v248
	v_mul_f32_e32 v30, v30, v248
	v_mul_f32_e32 v31, v31, v248
	v_mul_f32_e32 v32, v32, v248
	v_mul_f32_e32 v33, v33, v248
	v_mul_f32_e32 v2, v2, v248
	v_mul_f32_e32 v3, v3, v248
	v_mul_f32_e32 v4, v4, v248
	v_mul_f32_e32 v5, v5, v248
	v_mul_f32_e32 v6, v6, v248
	v_mul_f32_e32 v7, v7, v248
	v_mul_f32_e32 v8, v8, v248
	v_mul_f32_e32 v9, v9, v248
	v_mul_f32_e32 v10, v10, v248
	v_mul_f32_e32 v11, v11, v248
	v_mul_f32_e32 v12, v12, v248
	v_mul_f32_e32 v13, v13, v248
	v_mul_f32_e32 v14, v14, v248
	v_mul_f32_e32 v15, v15, v248
	v_mul_f32_e32 v16, v16, v248
	v_mul_f32_e32 v17, v17, v248
	v_mul_f32_e32 v50, v50, v248
	v_mul_f32_e32 v51, v51, v248
	v_mul_f32_e32 v52, v52, v248
	v_mul_f32_e32 v53, v53, v248
	v_mul_f32_e32 v54, v54, v248
	v_mul_f32_e32 v55, v55, v248
	v_mul_f32_e32 v56, v56, v248
	v_mul_f32_e32 v57, v57, v248
	v_mul_f32_e32 v58, v58, v248
	v_mul_f32_e32 v59, v59, v248
	v_mul_f32_e32 v60, v60, v248
	v_mul_f32_e32 v61, v61, v248
	v_mul_f32_e32 v62, v62, v248
	v_mul_f32_e32 v63, v63, v248
	v_mul_f32_e32 v64, v64, v248
	v_mul_f32_e32 v65, v65, v248
	s_branch .Lat_post_2
.Lat_exit:
	s_waitcnt lgkmcnt(0)
	v_mov_b64_e32 v[66:67], v[82:83]
	v_mov_b64_e32 v[68:69], v[84:85]
	v_mov_b64_e32 v[70:71], v[86:87]
	v_mov_b64_e32 v[72:73], v[88:89]
	v_mov_b64_e32 v[74:75], v[90:91]
	v_mov_b64_e32 v[76:77], v[92:93]
	v_mov_b64_e32 v[78:79], v[94:95]
	v_mov_b64_e32 v[80:81], v[96:97]
	v_mov_b64_e32 v[82:83], v[98:99]
	v_mov_b64_e32 v[84:85], v[100:101]
	v_mov_b64_e32 v[86:87], v[102:103]
	v_mov_b64_e32 v[88:89], v[104:105]
	v_mov_b64_e32 v[90:91], v[106:107]
	v_mov_b64_e32 v[92:93], v[108:109]
	v_mov_b64_e32 v[94:95], v[110:111]
	v_mov_b64_e32 v[96:97], v[112:113]
	v_add_f32_e32 v195, v197, v207
	v_mov_b32_e32 v204, 0
	v_mov_b32_e32 v196, 0x1a410
	v_lshl_add_u32 v196, v0, 2, v196
	ds_read_b32 v170, v196 offset:0
	ds_read_b32 v171, v196 offset:2048
	ds_read_b32 v172, v196 offset:4096
	ds_read_b32 v173, v196 offset:6144
	ds_read_b32 v174, v196 offset:8192
	ds_read_b32 v175, v196 offset:10240
	ds_read_b32 v176, v196 offset:12288
	ds_read_b32 v177, v196 offset:14336
	s_mov_b32 s7, 1
	s_mov_b32 s42, 2
	s_mov_b32 s4, 0x11800
	s_mov_b32 s8, 0x8c10
	s_movk_i32 s6, 0x83
	s_waitcnt lgkmcnt(0)
	s_branch .LBB0_400
